# softmax row max across lane halves: ds_bpermute round trip replaced by v_permlane32_swap (8 sites)
# baseline (speedup 1.0000x reference)
; template <int NDT, int MODE, bool ALLON>
; DI void attn_tile(const bf16_t* Kl, int kst, const bf16_t* Vl, const bf16x8 (&q)[4], f32x16 (&O)[NDT], float& m, float& l,
;                   int kbase, int qp, int win, float cbias, const float* tab, bool lane_on) {
;     ...
;   for (int ks = 0; ks < 4; ++ks) {
;     const bf16x8 k0 = *(const bf16x8*)(Kl + lr * kst + ks * 16 + lh * 8);
;     const bf16x8 k1 = *(const bf16x8*)(Kl + (32 + lr) * kst + ks * 16 + lh * 8);
;     s[0] = MFMA32(k0, q[ks], s[0]);
;     s[1] = MFMA32(k1, q[ks], s[1]);
;   }
;   float alpha, psum = 0.f;
;   if (MODE == 0) {
;     float tmax = fmaxf(s[0][0], s[1][0]);
; #pragma unroll
;     for (int i = 1; i < 16; ++i) tmax = fmaxf(tmax, fmaxf(s[0][i], s[1][i]));
;     tmax = fmaxf(tmax, xor32(tmax)) + cbias;
;     if (!ALLON) tmax = lane_on ? tmax : -1e30f;
;     const float mn = fmaxf(m, tmax);
;     alpha = ex2(m - mn);
;     m = mn;
;     const float mc = (ALLON || lane_on) ? mn - cbias : 1e30f;
; #pragma unroll
;     for (int st = 0; st < 2; ++st)
; #pragma unroll
;       for (int i = 0; i < 16; ++i) { const float pe = ex2(s[st][i] - mc); psum += pe; s[st][i] = pe; }
;   } else {
;     float tmax = -1e30f;
; #pragma unroll
;     for (int st = 0; st < 2; ++st)
; #pragma unroll
;       for (int i = 0; i < 16; ++i) {
;         const int key = kbase + st * 32 + 8 * (i >> 2) + 4 * lh + (i & 3);
;         float v;
;         if (MODE == 1) {
;           const int dist = qp - key;
;           const bool ok = (ALLON || lane_on) && dist >= 0 && dist < win;
;           const int di = dist < 0 ? 0 : (dist > 128 ? 128 : dist);
;           v = ok ? s[st][i] + tab[di] : -1e30f;
;         } else {
;           v = (16 * key + 31 <= qp) ? s[st][i] : -1e30f;
;         }
;         s[st][i] = v;
;         tmax = fmaxf(tmax, v);
;       }
;     tmax = fmaxf(tmax, xor32(tmax));
;     const float mn = fmaxf(m, tmax);
;     alpha = ex2(m - mn);
;     m = mn;
; #pragma unroll
;     for (int st = 0; st < 2; ++st)
; #pragma unroll
;       for (int i = 0; i < 16; ++i) {
;         const float pe = s[st][i] > -5e29f ? ex2(s[st][i] - mn) : 0.f;
;         psum += pe;
;         s[st][i] = pe;
;       }
;   }
;   l = l * alpha + psum;
;   if (__ballot(alpha != 1.f)) {
; #pragma unroll
;     for (int dt = 0; dt < NDT; ++dt)
; #pragma unroll
;       for (int i = 0; i < 16; ++i) O[dt][i] *= alpha;
.LBB0_668:
	v_mov_b32_e32 v32, v195
	s_waitcnt lgkmcnt(0)
	s_barrier
	s_nop 0
	v_and_b32_e32 v33, 31, v32
	v_bfe_u32 v141, v32, 5, 1
	v_mul_u32_u24_e32 v32, 0x48, v33
	v_lshlrev_b32_e32 v139, 1, v32
	v_lshlrev_b32_e32 v32, 4, v141
	v_add3_u32 v91, s7, v139, v32
	ds_read_b128 v[32:35], v91 offset:4608
	ds_read_b128 v[36:39], v91
	ds_read_b128 v[142:145], v91 offset:32
	s_waitcnt lgkmcnt(1)
	v_mfma_f32_32x32x16_bf16 v[48:63], v[36:39], v[64:67], 0
	ds_read_b128 v[146:149], v91 offset:4640
	v_mfma_f32_32x32x16_bf16 v[32:47], v[32:35], v[64:67], 0
	s_waitcnt lgkmcnt(1)
	v_mfma_f32_32x32x16_bf16 v[48:63], v[142:145], v[68:71], v[48:63]
	s_waitcnt lgkmcnt(0)
	v_mfma_f32_32x32x16_bf16 v[32:47], v[146:149], v[68:71], v[32:47]
	ds_read_b128 v[142:145], v91 offset:64
	ds_read_b128 v[146:149], v91 offset:4672
	s_waitcnt lgkmcnt(1)
	v_mfma_f32_32x32x16_bf16 v[48:63], v[142:145], v[72:75], v[48:63]
	s_waitcnt lgkmcnt(0)
	v_mfma_f32_32x32x16_bf16 v[32:47], v[146:149], v[72:75], v[32:47]
	ds_read_b128 v[142:145], v91 offset:96
	ds_read_b128 v[146:149], v91 offset:4704
	v_lshl_add_u32 v91, v141, 6, s5
	s_waitcnt lgkmcnt(1)
	v_mfma_f32_32x32x16_bf16 v[48:63], v[142:145], v[76:79], v[48:63]
	v_add_u32_e32 v142, 0xfffffc50, v91
	v_cmp_le_i32_e32 vcc, v142, v135
	s_waitcnt lgkmcnt(0)
	v_mfma_f32_32x32x16_bf16 v[32:47], v[146:149], v[76:79], v[32:47]
	s_nop 7
	v_cndmask_b32_e32 v152, v232, v48, vcc
	v_add_u32_e32 v48, 0xfffffc60, v91
	v_cmp_le_i32_e32 vcc, v48, v135
	s_nop 1
	v_cndmask_b32_e32 v153, v232, v49, vcc
	v_add_u32_e32 v49, 0xfffffc70, v91
	v_cmp_le_i32_e32 vcc, v49, v135
	v_add_u32_e32 v49, 0xfffffc80, v91
	v_max3_f32 v48, v152, s93, v153
	v_cndmask_b32_e32 v150, v232, v50, vcc
	v_cmp_le_i32_e32 vcc, v49, v135
	v_add_u32_e32 v49, 0xfffffcd0, v91
	s_nop 0
	v_cndmask_b32_e32 v148, v232, v51, vcc
	v_cmp_le_i32_e32 vcc, v49, v135
	v_add_u32_e32 v49, 0xfffffce0, v91
	v_max3_f32 v48, v48, v150, v148
	v_cndmask_b32_e32 v147, v232, v52, vcc
	v_cmp_le_i32_e32 vcc, v49, v135
	v_add_u32_e32 v49, 0xfffffcf0, v91
	s_nop 0
	v_cndmask_b32_e32 v145, v232, v53, vcc
	v_cmp_le_i32_e32 vcc, v49, v135
	v_add_u32_e32 v49, 0xfffffd00, v91
	v_max3_f32 v48, v48, v147, v145
	v_cndmask_b32_e32 v144, v232, v54, vcc
	v_cmp_le_i32_e32 vcc, v49, v135
	v_add_u32_e32 v49, 0xfffffd50, v91
	s_nop 0
	v_cndmask_b32_e32 v154, v232, v55, vcc
	v_cmp_le_i32_e32 vcc, v49, v135
	v_add_u32_e32 v49, 0xfffffd60, v91
	v_max3_f32 v48, v48, v144, v154
	v_cndmask_b32_e32 v151, v232, v56, vcc
	v_cmp_le_i32_e32 vcc, v49, v135
	v_add_u32_e32 v49, 0xfffffd70, v91
	s_nop 0
	v_cndmask_b32_e32 v149, v232, v57, vcc
	v_cmp_le_i32_e32 vcc, v49, v135
	v_add_u32_e32 v49, 0xfffffd80, v91
	v_max3_f32 v48, v48, v151, v149
	v_cndmask_b32_e32 v146, v232, v58, vcc
	v_cmp_le_i32_e32 vcc, v49, v135
	v_add_u32_e32 v49, 0xfffffdd0, v91
	s_nop 0
	v_cndmask_b32_e32 v143, v232, v59, vcc
	v_cmp_le_i32_e32 vcc, v49, v135
	v_add_u32_e32 v49, 0xfffffde0, v91
	v_max3_f32 v48, v48, v146, v143
	v_cndmask_b32_e32 v142, v232, v60, vcc
	v_cmp_le_i32_e32 vcc, v49, v135
	v_add_u32_e32 v49, 0xfffffdf0, v91
	s_nop 0
	v_cndmask_b32_e32 v57, v232, v61, vcc
	v_cmp_le_i32_e32 vcc, v49, v135
	v_add_u32_e32 v49, 0xfffffe00, v91
	v_max3_f32 v48, v48, v142, v57
	v_cndmask_b32_e32 v60, v232, v62, vcc
	v_cmp_le_i32_e32 vcc, v49, v135
	v_add_u32_e32 v49, 0xfffffe50, v91
	s_nop 0
	v_cndmask_b32_e32 v61, v232, v63, vcc
	v_cmp_le_i32_e32 vcc, v49, v135
	v_max3_f32 v48, v48, v60, v61
	s_nop 0
	v_cndmask_b32_e32 v58, v232, v32, vcc
	v_add_u32_e32 v32, 0xfffffe60, v91
	v_cmp_le_i32_e32 vcc, v32, v135
	s_nop 1
	v_cndmask_b32_e32 v55, v232, v33, vcc
	v_add_u32_e32 v33, 0xfffffe70, v91
	v_cmp_le_i32_e32 vcc, v33, v135
	v_add_u32_e32 v33, 0xfffffe80, v91
	v_max3_f32 v32, v48, v58, v55
	v_cndmask_b32_e32 v54, v232, v34, vcc
	v_cmp_le_i32_e32 vcc, v33, v135
	v_add_u32_e32 v33, 0xfffffed0, v91
	v_and_b32_e32 v34, 64, v231
	v_cndmask_b32_e32 v53, v232, v35, vcc
	v_cmp_le_i32_e32 vcc, v33, v135
	v_add_u32_e32 v33, 0xfffffee0, v91
	v_max3_f32 v32, v32, v54, v53
	v_cndmask_b32_e32 v52, v232, v36, vcc
	v_cmp_le_i32_e32 vcc, v33, v135
	v_add_u32_e32 v33, 0xfffffef0, v91
	v_add_u32_e32 v34, 64, v34
	v_cndmask_b32_e32 v51, v232, v37, vcc
	v_cmp_le_i32_e32 vcc, v33, v135
	v_add_u32_e32 v33, 0xffffff00, v91
	v_max3_f32 v32, v32, v52, v51
	v_cndmask_b32_e32 v50, v232, v38, vcc
	v_cmp_le_i32_e32 vcc, v33, v135
	v_add_u32_e32 v33, 0xffffff50, v91
	s_nop 0
	v_cndmask_b32_e32 v49, v232, v39, vcc
	v_cmp_le_i32_e32 vcc, v33, v135
	v_add_u32_e32 v33, 0xffffff60, v91
	v_max3_f32 v32, v32, v50, v49
	v_cndmask_b32_e32 v48, v232, v40, vcc
	v_cmp_le_i32_e32 vcc, v33, v135
	v_add_u32_e32 v33, 0xffffff70, v91
	s_nop 0
	v_cndmask_b32_e32 v41, v232, v41, vcc
	v_cmp_le_i32_e32 vcc, v33, v135
	v_add_u32_e32 v33, 0xffffff80, v91
	v_max3_f32 v32, v32, v48, v41
	v_cndmask_b32_e32 v40, v232, v42, vcc
	v_cmp_le_i32_e32 vcc, v33, v135
	v_subrev_u32_e32 v33, 48, v91
	s_nop 0
	v_cndmask_b32_e32 v39, v232, v43, vcc
	v_cmp_le_i32_e32 vcc, v33, v135
	v_subrev_u32_e32 v33, 32, v91
	v_max3_f32 v32, v32, v40, v39
	v_cndmask_b32_e32 v38, v232, v44, vcc
	v_cmp_le_i32_e32 vcc, v33, v135
	v_add_u32_e32 v33, -16, v91
	s_nop 0
	v_cndmask_b32_e32 v37, v232, v45, vcc
	v_cmp_le_i32_e32 vcc, v33, v135
	v_xor_b32_e32 v33, 32, v231
	v_max3_f32 v32, v32, v38, v37
	v_cndmask_b32_e32 v36, v232, v46, vcc
	v_cmp_le_i32_e32 vcc, v91, v135
	s_nop 1
	v_cndmask_b32_e32 v35, v232, v47, vcc
	v_cmp_lt_i32_e32 vcc, v33, v34
	v_max3_f32 v32, v32, v36, v35
	s_nop 0
	v_cndmask_b32_e32 v33, v231, v33, vcc
	v_lshlrev_b32_e32 v91, 2, v33
	v_mov_b32_e32 v33, v32
	s_nop 1
	v_permlane32_swap_b32_e32 v33, v32
	s_waitcnt lgkmcnt(0)
	v_max_f32_e32 v32, v32, v33
	v_add_f32_e32 v33, 0x41000000, v140
	v_cmp_gt_f32_e32 vcc, v32, v33
	s_nop 1
	v_cndmask_b32_e32 v33, v140, v32, vcc
	v_sub_f32_e32 v32, v140, v33
	v_exp_f32_e32 v32, v32
	s_nop 0
	v_cmp_neq_f32_e32 vcc, 1.0, v32
	s_cbranch_vccz .LBB0_670
	v_pk_mul_f32 v[0:1], v[112:113], v[32:33] op_sel_hi:[1,0]
	v_pk_mul_f32 v[2:3], v[114:115], v[32:33] op_sel_hi:[1,0]
	v_pk_mul_f32 v[4:5], v[116:117], v[32:33] op_sel_hi:[1,0]
	v_pk_mul_f32 v[6:7], v[118:119], v[32:33] op_sel_hi:[1,0]
	v_pk_mul_f32 v[8:9], v[120:121], v[32:33] op_sel_hi:[1,0]
	v_pk_mul_f32 v[10:11], v[122:123], v[32:33] op_sel_hi:[1,0]
	v_pk_mul_f32 v[12:13], v[124:125], v[32:33] op_sel_hi:[1,0]
	v_pk_mul_f32 v[14:15], v[126:127], v[32:33] op_sel_hi:[1,0]
	v_pk_mul_f32 v[16:17], v[96:97], v[32:33] op_sel_hi:[1,0]
	v_pk_mul_f32 v[18:19], v[98:99], v[32:33] op_sel_hi:[1,0]
	v_pk_mul_f32 v[20:21], v[100:101], v[32:33] op_sel_hi:[1,0]
	v_pk_mul_f32 v[22:23], v[102:103], v[32:33] op_sel_hi:[1,0]
	v_pk_mul_f32 v[24:25], v[104:105], v[32:33] op_sel_hi:[1,0]
	v_pk_mul_f32 v[26:27], v[106:107], v[32:33] op_sel_hi:[1,0]
	v_pk_mul_f32 v[28:29], v[108:109], v[32:33] op_sel_hi:[1,0]
	v_pk_mul_f32 v[30:31], v[110:111], v[32:33] op_sel_hi:[1,0]

; template <int NDT, int MODE, bool ALLON>
; DI void attn_tile(const bf16_t* Kl, int kst, const bf16_t* Vl, const bf16x8 (&q)[4], f32x16 (&O)[NDT], float& m, float& l,
;                   int kbase, int qp, int win, float cbias, const float* tab, bool lane_on) {
;     ...
;   for (int ks = 0; ks < 4; ++ks) {
;     const bf16x8 k0 = *(const bf16x8*)(Kl + lr * kst + ks * 16 + lh * 8);
;     const bf16x8 k1 = *(const bf16x8*)(Kl + (32 + lr) * kst + ks * 16 + lh * 8);
;     s[0] = MFMA32(k0, q[ks], s[0]);
;     s[1] = MFMA32(k1, q[ks], s[1]);
;   }
;   float alpha, psum = 0.f;
;   if (MODE == 0) {
;     float tmax = fmaxf(s[0][0], s[1][0]);
; #pragma unroll
;     for (int i = 1; i < 16; ++i) tmax = fmaxf(tmax, fmaxf(s[0][i], s[1][i]));
;     tmax = fmaxf(tmax, xor32(tmax)) + cbias;
;     if (!ALLON) tmax = lane_on ? tmax : -1e30f;
;     const float mn = fmaxf(m, tmax);
;     alpha = ex2(m - mn);
;     m = mn;
;     const float mc = (ALLON || lane_on) ? mn - cbias : 1e30f;
; #pragma unroll
;     for (int st = 0; st < 2; ++st)
; #pragma unroll
;       for (int i = 0; i < 16; ++i) { const float pe = ex2(s[st][i] - mc); psum += pe; s[st][i] = pe; }
;   } else {
;     float tmax = -1e30f;
; #pragma unroll
;     for (int st = 0; st < 2; ++st)
; #pragma unroll
;       for (int i = 0; i < 16; ++i) {
;         const int key = kbase + st * 32 + 8 * (i >> 2) + 4 * lh + (i & 3);
;         float v;
;         if (MODE == 1) {
;           const int dist = qp - key;
;           const bool ok = (ALLON || lane_on) && dist >= 0 && dist < win;
;           const int di = dist < 0 ? 0 : (dist > 128 ? 128 : dist);
;           v = ok ? s[st][i] + tab[di] : -1e30f;
;         } else {
;           v = (16 * key + 31 <= qp) ? s[st][i] : -1e30f;
;         }
;         s[st][i] = v;
;         tmax = fmaxf(tmax, v);
;       }
;     tmax = fmaxf(tmax, xor32(tmax));
;     const float mn = fmaxf(m, tmax);
;     alpha = ex2(m - mn);
;     m = mn;
; #pragma unroll
;     for (int st = 0; st < 2; ++st)
; #pragma unroll
;       for (int i = 0; i < 16; ++i) {
;         const float pe = s[st][i] > -5e29f ? ex2(s[st][i] - mn) : 0.f;
;         psum += pe;
;         s[st][i] = pe;
;       }
;   }
;   l = l * alpha + psum;
;   if (__ballot(alpha != 1.f)) {
; #pragma unroll
;     for (int dt = 0; dt < NDT; ++dt)
; #pragma unroll
;       for (int i = 0; i < 16; ++i) O[dt][i] *= alpha;
.LBB0_720:
	v_ffbl_b32_e32 v1, v1
	v_ffbl_b32_e32 v0, v0
	v_add_u32_e64 v1, v1, 32 clamp
	v_min_u32_e32 v0, v1, v0
	v_lshlrev_b32_e32 v32, 6, v0
	v_cmp_le_i32_e32 vcc, v32, v138
	s_waitcnt lgkmcnt(0)
	s_barrier
	s_and_saveexec_b64 s[8:9], vcc
	s_cbranch_execz .LBB0_797
	v_lshrrev_b64 v[0:1], v0, v[96:97]
	v_and_b32_e32 v0, 1, v0
	v_cmp_eq_u32_e64 s[4:5], 1, v0
	v_cmp_ne_u32_e32 vcc, 0, v0
	s_cbranch_vccz .LBB0_797
	v_cmp_le_i32_e32 vcc, v32, v137
	s_and_saveexec_b64 s[28:29], vcc
	s_xor_b64 s[28:29], exec, s[28:29]
	s_cbranch_execz .LBB0_727
	v_mov_b32_e32 v0, v195
	ds_read_b32 v144, v135 offset:37376
	s_nop 0
	v_and_b32_e32 v1, 31, v0
	v_lshrrev_b32_e32 v0, 2, v0
	v_mul_u32_u24_e32 v1, 0x48, v1
	v_and_b32_e32 v143, 8, v0
	v_lshlrev_b32_e32 v142, 1, v1
	v_lshlrev_b32_e32 v0, 1, v143
	v_add3_u32 v4, s45, v142, v0
	ds_read_b128 v[196:199], v4
	ds_read_b128 v[200:203], v4 offset:4608
	ds_read_b128 v[204:207], v4 offset:32
	ds_read_b128 v[208:211], v4 offset:4640
	ds_read_b128 v[212:215], v4 offset:64
	ds_read_b128 v[216:219], v4 offset:4672
	ds_read_b128 v[152:155], v4 offset:4704
	ds_read_b128 v[156:159], v4 offset:96
	s_waitcnt lgkmcnt(8)
	v_sub_f32_e32 v145, v144, v88
	v_cmp_neq_f32_e32 vcc, v88, v232
	s_nop 1
	v_cndmask_b32_e32 v145, 0, v145, vcc
	v_cndmask_b32_e64 v145, v232, v145, s[4:5]
	v_mov_b32_e32 v236, v145
	v_mov_b32_e32 v237, v145
	v_mov_b32_e32 v238, v145
	v_mov_b32_e32 v239, v145
	v_mov_b32_e32 v240, v145
	v_mov_b32_e32 v241, v145
	v_mov_b32_e32 v242, v145
	v_mov_b32_e32 v243, v145
	v_mov_b32_e32 v244, v145
	v_mov_b32_e32 v245, v145
	v_mov_b32_e32 v246, v145
	v_mov_b32_e32 v247, v145
	v_mov_b32_e32 v248, v145
	v_mov_b32_e32 v249, v145
	v_mov_b32_e32 v250, v145
	v_mov_b32_e32 v251, v145
	s_nop 1
	s_waitcnt lgkmcnt(7)
	v_mfma_f32_32x32x16_bf16 v[48:63], v[196:199], v[64:67], v[236:251]
	s_waitcnt lgkmcnt(6)
	v_mfma_f32_32x32x16_bf16 v[32:47], v[200:203], v[64:67], v[236:251]
	s_waitcnt lgkmcnt(5)
	v_mfma_f32_32x32x16_bf16 v[48:63], v[204:207], v[68:71], v[48:63]
	s_waitcnt lgkmcnt(4)
	v_mfma_f32_32x32x16_bf16 v[32:47], v[208:211], v[68:71], v[32:47]
	s_waitcnt lgkmcnt(3)
	v_mfma_f32_32x32x16_bf16 v[48:63], v[212:215], v[72:75], v[48:63]
	s_waitcnt lgkmcnt(2)
	v_mfma_f32_32x32x16_bf16 v[32:47], v[216:219], v[72:75], v[32:47]
	s_waitcnt lgkmcnt(1)
	v_mfma_f32_32x32x16_bf16 v[32:47], v[152:155], v[76:79], v[32:47]
	s_waitcnt lgkmcnt(0)
	v_mfma_f32_32x32x16_bf16 v[48:63], v[156:159], v[76:79], v[48:63]
	s_nop 8
	v_max3_f32 v0, v32, v33, v34
	v_max3_f32 v0, v0, v35, v36
	v_max3_f32 v0, v0, v37, v38
	v_max3_f32 v0, v0, v39, v40
	v_max3_f32 v0, v0, v41, v42
	v_max3_f32 v0, v0, v43, v44
	v_max3_f32 v0, v0, v45, v46
	v_max_f32_e32 v0, v0, v47
	v_max3_f32 v1, v48, v49, v50
	v_max3_f32 v1, v1, v51, v52
	v_max3_f32 v1, v1, v53, v54
	v_max3_f32 v1, v1, v55, v56
	v_max3_f32 v1, v1, v57, v58
	v_max3_f32 v1, v1, v59, v60
	v_max3_f32 v1, v1, v61, v62
	v_max_f32_e32 v1, v1, v63
	v_max_f32_e32 v0, v0, v1
	v_mov_b32_e32 v1, v0
	s_nop 1
	v_permlane32_swap_b32_e32 v1, v0
	s_waitcnt lgkmcnt(0)
	v_max_f32_e32 v0, v0, v1
	v_cmp_lt_f32_e32 vcc, 0x41000000, v0
	v_cmp_eq_f32_e64 s[48:49], v88, v232
	s_nop 1
	s_and_b64 s[48:49], s[48:49], s[4:5]
	s_or_b64 s[50:51], vcc, s[48:49]
	s_cbranch_scc0 .Lsel_fast
	v_sub_f32_e32 v48, v48, v145
	v_sub_f32_e32 v49, v49, v145
	v_sub_f32_e32 v50, v50, v145
	v_sub_f32_e32 v51, v51, v145
	v_sub_f32_e32 v52, v52, v145
	v_sub_f32_e32 v53, v53, v145
	v_sub_f32_e32 v54, v54, v145
	v_sub_f32_e32 v55, v55, v145
	v_sub_f32_e32 v56, v56, v145
	v_sub_f32_e32 v57, v57, v145
	v_sub_f32_e32 v58, v58, v145
	v_sub_f32_e32 v59, v59, v145
	v_sub_f32_e32 v60, v60, v145
	v_sub_f32_e32 v61, v61, v145
	v_sub_f32_e32 v62, v62, v145
	v_sub_f32_e32 v63, v63, v145
	v_sub_f32_e32 v32, v32, v145
	v_sub_f32_e32 v33, v33, v145
	v_sub_f32_e32 v34, v34, v145
	v_sub_f32_e32 v35, v35, v145
	v_sub_f32_e32 v36, v36, v145
	v_sub_f32_e32 v37, v37, v145
	v_sub_f32_e32 v38, v38, v145
	v_sub_f32_e32 v39, v39, v145
	v_sub_f32_e32 v40, v40, v145
	v_sub_f32_e32 v41, v41, v145
	v_sub_f32_e32 v42, v42, v145
	v_sub_f32_e32 v43, v43, v145
	v_sub_f32_e32 v44, v44, v145
	v_sub_f32_e32 v45, v45, v145
	v_sub_f32_e32 v46, v46, v145
	v_sub_f32_e32 v47, v47, v145
	v_sub_f32_e32 v0, v0, v145
	v_add_f32_e32 v0, v144, v0
	v_cndmask_b32_e64 v0, v232, v0, s[4:5]
	v_add_f32_e32 v1, 0x41000000, v88
	v_cmp_gt_f32_e32 vcc, v0, v1
	s_nop 1
	v_cndmask_b32_e32 v141, v88, v0, vcc
	v_sub_f32_e32 v0, v88, v141
	v_exp_f32_e32 v88, v0
	s_nop 0
	v_cmp_neq_f32_e32 vcc, 1.0, v88
	s_cbranch_vccz .LBB0_799
	v_pk_mul_f32 v[160:161], v[160:161], v[88:89] op_sel_hi:[1,0]
	v_pk_mul_f32 v[162:163], v[162:163], v[88:89] op_sel_hi:[1,0]
	v_pk_mul_f32 v[164:165], v[164:165], v[88:89] op_sel_hi:[1,0]
	v_pk_mul_f32 v[166:167], v[166:167], v[88:89] op_sel_hi:[1,0]
	v_pk_mul_f32 v[168:169], v[168:169], v[88:89] op_sel_hi:[1,0]
	v_pk_mul_f32 v[170:171], v[170:171], v[88:89] op_sel_hi:[1,0]
	v_pk_mul_f32 v[172:173], v[172:173], v[88:89] op_sel_hi:[1,0]
	v_pk_mul_f32 v[174:175], v[174:175], v[88:89] op_sel_hi:[1,0]
	v_pk_mul_f32 v[176:177], v[176:177], v[88:89] op_sel_hi:[1,0]
	v_pk_mul_f32 v[178:179], v[178:179], v[88:89] op_sel_hi:[1,0]
	v_pk_mul_f32 v[180:181], v[180:181], v[88:89] op_sel_hi:[1,0]
	v_pk_mul_f32 v[182:183], v[182:183], v[88:89] op_sel_hi:[1,0]
	v_pk_mul_f32 v[184:185], v[184:185], v[88:89] op_sel_hi:[1,0]
	v_pk_mul_f32 v[186:187], v[186:187], v[88:89] op_sel_hi:[1,0]
	v_pk_mul_f32 v[188:189], v[188:189], v[88:89] op_sel_hi:[1,0]
	v_pk_mul_f32 v[190:191], v[190:191], v[88:89] op_sel_hi:[1,0]
	s_cbranch_execnz .LBB0_726

; template <int NDT, int MODE, bool ALLON>
; DI void attn_tile(const bf16_t* Kl, int kst, const bf16_t* Vl, const bf16x8 (&q)[4], f32x16 (&O)[NDT], float& m, float& l,
;                   int kbase, int qp, int win, float cbias, const float* tab, bool lane_on) {
;     ...
;   for (int ks = 0; ks < 4; ++ks) {
;     const bf16x8 k0 = *(const bf16x8*)(Kl + lr * kst + ks * 16 + lh * 8);
;     const bf16x8 k1 = *(const bf16x8*)(Kl + (32 + lr) * kst + ks * 16 + lh * 8);
;     s[0] = MFMA32(k0, q[ks], s[0]);
;     s[1] = MFMA32(k1, q[ks], s[1]);
;   }
;   float alpha, psum = 0.f;
;   if (MODE == 0) {
;     float tmax = fmaxf(s[0][0], s[1][0]);
; #pragma unroll
;     for (int i = 1; i < 16; ++i) tmax = fmaxf(tmax, fmaxf(s[0][i], s[1][i]));
;     tmax = fmaxf(tmax, xor32(tmax)) + cbias;
;     if (!ALLON) tmax = lane_on ? tmax : -1e30f;
;     const float mn = fmaxf(m, tmax);
;     alpha = ex2(m - mn);
;     m = mn;
;     const float mc = (ALLON || lane_on) ? mn - cbias : 1e30f;
; #pragma unroll
;     for (int st = 0; st < 2; ++st)
; #pragma unroll
;       for (int i = 0; i < 16; ++i) { const float pe = ex2(s[st][i] - mc); psum += pe; s[st][i] = pe; }
;   } else {
;     float tmax = -1e30f;
; #pragma unroll
;     for (int st = 0; st < 2; ++st)
; #pragma unroll
;       for (int i = 0; i < 16; ++i) {
;         const int key = kbase + st * 32 + 8 * (i >> 2) + 4 * lh + (i & 3);
;         float v;
;         if (MODE == 1) {
;           const int dist = qp - key;
;           const bool ok = (ALLON || lane_on) && dist >= 0 && dist < win;
;           const int di = dist < 0 ? 0 : (dist > 128 ? 128 : dist);
;           v = ok ? s[st][i] + tab[di] : -1e30f;
;         } else {
;           v = (16 * key + 31 <= qp) ? s[st][i] : -1e30f;
;         }
;         s[st][i] = v;
;         tmax = fmaxf(tmax, v);
;       }
;     tmax = fmaxf(tmax, xor32(tmax));
;     const float mn = fmaxf(m, tmax);
;     alpha = ex2(m - mn);
;     m = mn;
; #pragma unroll
;     for (int st = 0; st < 2; ++st)
; #pragma unroll
;       for (int i = 0; i < 16; ++i) {
;         const float pe = s[st][i] > -5e29f ? ex2(s[st][i] - mn) : 0.f;
;         psum += pe;
;         s[st][i] = pe;
;       }
;   }
;   l = l * alpha + psum;
;   if (__ballot(alpha != 1.f)) {
; #pragma unroll
;     for (int dt = 0; dt < NDT; ++dt)
; #pragma unroll
;       for (int i = 0; i < 16; ++i) O[dt][i] *= alpha;
.LBB0_727:
	s_andn2_saveexec_b64 s[28:29], s[28:29]
	s_cbranch_execz .LBB0_796
	s_nop 6
	v_mov_b32_e32 v0, v195
	v_mov_b32_e32 v55, 0xf149f2ca
	v_and_b32_e32 v1, 31, v0
	v_bfe_u32 v42, v0, 5, 1
	v_mul_u32_u24_e32 v0, 0x48, v1
	v_lshlrev_b32_e32 v33, 1, v0
	v_lshlrev_b32_e32 v0, 4, v42
	v_add3_u32 v43, s45, v33, v0
	ds_read_b128 v[0:3], v43 offset:4608
	ds_read_b128 v[4:7], v43
	ds_read_b128 v[34:37], v43 offset:32
	ds_read_b128 v[38:41], v43 offset:4640
	s_waitcnt lgkmcnt(2)
	v_mfma_f32_32x32x16_bf16 v[16:31], v[4:7], v[64:67], 0
	v_mov_b32_e32 v62, 0xf149f2ca
	v_mfma_f32_32x32x16_bf16 v[0:15], v[0:3], v[64:67], 0
	s_waitcnt lgkmcnt(1)
	v_mfma_f32_32x32x16_bf16 v[16:31], v[34:37], v[68:71], v[16:31]
	s_waitcnt lgkmcnt(0)
	v_mfma_f32_32x32x16_bf16 v[0:15], v[38:41], v[68:71], v[0:15]
	ds_read_b128 v[34:37], v43 offset:64
	ds_read_b128 v[38:41], v43 offset:4672
	s_waitcnt lgkmcnt(1)
	v_mfma_f32_32x32x16_bf16 v[16:31], v[34:37], v[72:75], v[16:31]
	s_waitcnt lgkmcnt(0)
	v_mfma_f32_32x32x16_bf16 v[0:15], v[38:41], v[72:75], v[0:15]
	ds_read_b128 v[34:37], v43 offset:96
	ds_read_b128 v[38:41], v43 offset:4704
	s_waitcnt lgkmcnt(1)
	v_mfma_f32_32x32x16_bf16 v[16:31], v[34:37], v[76:79], v[16:31]
	v_lshlrev_b32_e32 v34, 2, v42
	v_or_b32_e32 v32, v34, v32
	v_sub_u32_e32 v35, v134, v32
	v_bfe_u32 v245, v195, 6, 2
	v_lshlrev_b32_e32 v245, 12, v245
	v_add_u32_e32 v245, 0x1e014, v245
	v_lshl_add_u32 v244, v35, 2, v245
	v_subrev_u32_e32 v246, 20, v245
	v_cndmask_b32_e64 v244, v246, v244, s[4:5]
	s_waitcnt lgkmcnt(0)
	v_mfma_f32_32x32x16_bf16 v[0:15], v[38:41], v[76:79], v[0:15]
	ds_read2_b32 v[196:197], v244 offset0:59 offset1:58
	ds_read2_b32 v[198:199], v244 offset0:57 offset1:56
	ds_read2_b32 v[200:201], v244 offset0:51 offset1:50
	ds_read2_b32 v[202:203], v244 offset0:49 offset1:48
	ds_read2_b32 v[204:205], v244 offset0:43 offset1:42
	ds_read2_b32 v[206:207], v244 offset0:41 offset1:40
	ds_read2_b32 v[208:209], v244 offset0:35 offset1:34
	ds_read2_b32 v[210:211], v244 offset0:33 offset1:32
	ds_read2_b32 v[212:213], v244 offset0:27 offset1:26
	ds_read2_b32 v[214:215], v244 offset0:25 offset1:24
	ds_read2_b32 v[216:217], v244 offset0:19 offset1:18
	ds_read2_b32 v[218:219], v244 offset0:17 offset1:16
	ds_read2_b32 v[236:237], v244 offset0:11 offset1:10
	ds_read2_b32 v[238:239], v244 offset0:9 offset1:8
	ds_read2_b32 v[240:241], v244 offset0:3 offset1:2
	s_waitcnt lgkmcnt(14)
	v_add_f32_e32 v62, v16, v196
	v_add_f32_e32 v55, v17, v197
	ds_read2_b32 v[242:243], v244 offset0:1 offset1:0
	s_waitcnt lgkmcnt(14)
	v_add_f32_e32 v61, v18, v198
	v_add_f32_e32 v49, v19, v199
	s_waitcnt lgkmcnt(13)
	v_add_f32_e32 v60, v20, v200
	v_add_f32_e32 v47, v21, v201
	s_waitcnt lgkmcnt(12)
	v_add_f32_e32 v59, v22, v202
	v_add_f32_e32 v45, v23, v203
	s_waitcnt lgkmcnt(11)
	v_add_f32_e32 v58, v24, v204
	v_add_f32_e32 v43, v25, v205
	s_waitcnt lgkmcnt(10)
	v_add_f32_e32 v57, v26, v206
	v_add_f32_e32 v42, v27, v207
	s_waitcnt lgkmcnt(9)
	v_add_f32_e32 v56, v28, v208
	v_add_f32_e32 v41, v29, v209
	s_waitcnt lgkmcnt(8)
	v_add_f32_e32 v54, v30, v210
	v_add_f32_e32 v40, v31, v211
	s_waitcnt lgkmcnt(7)
	v_add_f32_e32 v52, v0, v212
	v_add_f32_e32 v39, v1, v213
	s_waitcnt lgkmcnt(6)
	v_add_f32_e32 v51, v2, v214
	v_add_f32_e32 v38, v3, v215
	s_waitcnt lgkmcnt(5)
	v_add_f32_e32 v48, v4, v216
	v_add_f32_e32 v37, v5, v217
	s_waitcnt lgkmcnt(4)
	v_add_f32_e32 v46, v6, v218
	v_add_f32_e32 v35, v7, v219
	s_waitcnt lgkmcnt(3)
	v_add_f32_e32 v44, v8, v236
	v_add_f32_e32 v36, v9, v237
	s_waitcnt lgkmcnt(2)
	v_add_f32_e32 v53, v10, v238
	v_add_f32_e32 v50, v11, v239
	s_waitcnt lgkmcnt(1)
	v_add_f32_e32 v142, v12, v240
	v_add_f32_e32 v63, v13, v241
	s_waitcnt lgkmcnt(0)
	v_add_f32_e32 v144, v14, v242
	v_add_f32_e32 v143, v15, v243
	v_max3_f32 v0, v62, s93, v55
	v_max3_f32 v0, v0, v61, v49
	v_max3_f32 v0, v0, v60, v47
	v_max3_f32 v0, v0, v59, v45
	v_max3_f32 v0, v0, v58, v43
	v_max3_f32 v0, v0, v57, v42
	v_max3_f32 v0, v0, v56, v41
	v_max3_f32 v0, v0, v54, v40
	v_max3_f32 v0, v0, v52, v39
	v_max3_f32 v0, v0, v51, v38
	v_max3_f32 v0, v0, v48, v37
	v_max3_f32 v0, v0, v46, v35
	v_max3_f32 v0, v0, v44, v36
	v_max3_f32 v0, v0, v53, v50
	v_max3_f32 v0, v0, v142, v63
	v_max3_f32 v0, v0, v144, v143
	v_mov_b32_e32 v1, v0
	s_nop 1
	v_permlane32_swap_b32_e32 v1, v0
	s_waitcnt lgkmcnt(0)
	v_max_f32_e32 v0, v0, v1
	v_add_f32_e32 v1, 0x41000000, v88
	v_cmp_gt_f32_e32 vcc, v0, v1
	s_nop 1
	v_cndmask_b32_e32 v141, v88, v0, vcc
	v_sub_f32_e32 v0, v88, v141
	v_exp_f32_e32 v32, v0
	s_nop 0
	v_cmp_neq_f32_e32 vcc, 1.0, v32
	s_cbranch_vccz .LBB0_800
	v_pk_mul_f32 v[160:161], v[160:161], v[32:33] op_sel_hi:[1,0]
	v_pk_mul_f32 v[162:163], v[162:163], v[32:33] op_sel_hi:[1,0]
	v_pk_mul_f32 v[164:165], v[164:165], v[32:33] op_sel_hi:[1,0]
	v_pk_mul_f32 v[166:167], v[166:167], v[32:33] op_sel_hi:[1,0]
	v_pk_mul_f32 v[168:169], v[168:169], v[32:33] op_sel_hi:[1,0]
	v_pk_mul_f32 v[170:171], v[170:171], v[32:33] op_sel_hi:[1,0]
	v_pk_mul_f32 v[172:173], v[172:173], v[32:33] op_sel_hi:[1,0]
	v_pk_mul_f32 v[174:175], v[174:175], v[32:33] op_sel_hi:[1,0]
	v_pk_mul_f32 v[176:177], v[176:177], v[32:33] op_sel_hi:[1,0]
	v_pk_mul_f32 v[178:179], v[178:179], v[32:33] op_sel_hi:[1,0]
	v_pk_mul_f32 v[180:181], v[180:181], v[32:33] op_sel_hi:[1,0]
	v_pk_mul_f32 v[182:183], v[182:183], v[32:33] op_sel_hi:[1,0]
	v_pk_mul_f32 v[184:185], v[184:185], v[32:33] op_sel_hi:[1,0]
	v_pk_mul_f32 v[186:187], v[186:187], v[32:33] op_sel_hi:[1,0]
	v_pk_mul_f32 v[188:189], v[188:189], v[32:33] op_sel_hi:[1,0]
	v_pk_mul_f32 v[190:191], v[190:191], v[32:33] op_sel_hi:[1,0]
	s_cbranch_execnz .LBB0_795

; template <int NDT, int MODE, bool ALLON>
; DI void attn_tile(const bf16_t* Kl, int kst, const bf16_t* Vl, const bf16x8 (&q)[4], f32x16 (&O)[NDT], float& m, float& l,
;                   int kbase, int qp, int win, float cbias, const float* tab, bool lane_on) {
;     ...
;   for (int ks = 0; ks < 4; ++ks) {
;     const bf16x8 k0 = *(const bf16x8*)(Kl + lr * kst + ks * 16 + lh * 8);
;     const bf16x8 k1 = *(const bf16x8*)(Kl + (32 + lr) * kst + ks * 16 + lh * 8);
;     s[0] = MFMA32(k0, q[ks], s[0]);
;     s[1] = MFMA32(k1, q[ks], s[1]);
;   }
;   float alpha, psum = 0.f;
;   if (MODE == 0) {
;     float tmax = fmaxf(s[0][0], s[1][0]);
; #pragma unroll
;     for (int i = 1; i < 16; ++i) tmax = fmaxf(tmax, fmaxf(s[0][i], s[1][i]));
;     tmax = fmaxf(tmax, xor32(tmax)) + cbias;
;     if (!ALLON) tmax = lane_on ? tmax : -1e30f;
;     const float mn = fmaxf(m, tmax);
;     alpha = ex2(m - mn);
;     m = mn;
;     const float mc = (ALLON || lane_on) ? mn - cbias : 1e30f;
; #pragma unroll
;     for (int st = 0; st < 2; ++st)
; #pragma unroll
;       for (int i = 0; i < 16; ++i) { const float pe = ex2(s[st][i] - mc); psum += pe; s[st][i] = pe; }
;   } else {
;     float tmax = -1e30f;
; #pragma unroll
;     for (int st = 0; st < 2; ++st)
; #pragma unroll
;       for (int i = 0; i < 16; ++i) {
;         const int key = kbase + st * 32 + 8 * (i >> 2) + 4 * lh + (i & 3);
;         float v;
;         if (MODE == 1) {
;           const int dist = qp - key;
;           const bool ok = (ALLON || lane_on) && dist >= 0 && dist < win;
;           const int di = dist < 0 ? 0 : (dist > 128 ? 128 : dist);
;           v = ok ? s[st][i] + tab[di] : -1e30f;
;         } else {
;           v = (16 * key + 31 <= qp) ? s[st][i] : -1e30f;
;         }
;         s[st][i] = v;
;         tmax = fmaxf(tmax, v);
;       }
;     tmax = fmaxf(tmax, xor32(tmax));
;     const float mn = fmaxf(m, tmax);
;     alpha = ex2(m - mn);
;     m = mn;
; #pragma unroll
;     for (int st = 0; st < 2; ++st)
; #pragma unroll
;       for (int i = 0; i < 16; ++i) {
;         const float pe = s[st][i] > -5e29f ? ex2(s[st][i] - mn) : 0.f;
;         psum += pe;
;         s[st][i] = pe;
;       }
;   }
;   l = l * alpha + psum;
;   if (__ballot(alpha != 1.f)) {
; #pragma unroll
;     for (int dt = 0; dt < NDT; ++dt)
; #pragma unroll
;       for (int i = 0; i < 16; ++i) O[dt][i] *= alpha;
.LBB0_810:
	v_cmp_le_i32_e32 vcc, s6, v138
	v_cmp_ge_i32_e64 s[0:1], s6, v127
	s_and_b64 s[0:1], vcc, s[0:1]
	s_waitcnt lgkmcnt(0)
	s_barrier
	s_and_saveexec_b64 s[28:29], s[0:1]
	s_cbranch_execz .LBB0_807
	v_cmp_gt_i32_e32 vcc, s6, v137
	v_cmp_le_i32_e64 s[0:1], s6, v128
	s_or_b64 s[0:1], vcc, s[0:1]
	s_and_saveexec_b64 s[30:31], s[0:1]
	s_xor_b64 s[0:1], exec, s[30:31]
	s_cbranch_execz .LBB0_880
	v_mov_b32_e32 v0, v195
	v_mov_b32_e32 v63, 0xf149f2ca
	v_and_b32_e32 v1, 31, v0
	v_bfe_u32 v34, v0, 5, 1
	v_mul_u32_u24_e32 v0, 0x48, v1
	v_lshlrev_b32_e32 v33, 1, v0
	v_lshlrev_b32_e32 v0, 4, v34
	v_add3_u32 v32, s25, v33, v0
	ds_read_b128 v[0:3], v32
	ds_read_b128 v[36:39], v32 offset:32
	v_mov_b32_e32 v134, 0xf149f2ca
	s_waitcnt lgkmcnt(1)
	v_mfma_f32_32x32x16_bf16 v[16:31], v[0:3], v[64:67], 0
	ds_read_b128 v[0:3], v32 offset:4608
	s_waitcnt lgkmcnt(1)
	v_mfma_f32_32x32x16_bf16 v[16:31], v[36:39], v[68:71], v[16:31]
	ds_read_b128 v[36:39], v32 offset:4640
	s_waitcnt lgkmcnt(1)
	v_mfma_f32_32x32x16_bf16 v[0:15], v[0:3], v[64:67], 0
	s_waitcnt lgkmcnt(0)
	v_mfma_f32_32x32x16_bf16 v[0:15], v[36:39], v[68:71], v[0:15]
	ds_read_b128 v[36:39], v32 offset:64
	s_waitcnt lgkmcnt(0)
	v_mfma_f32_32x32x16_bf16 v[16:31], v[36:39], v[72:75], v[16:31]
	ds_read_b128 v[36:39], v32 offset:4672
	s_waitcnt lgkmcnt(0)
	v_mfma_f32_32x32x16_bf16 v[0:15], v[36:39], v[72:75], v[0:15]
	ds_read_b128 v[36:39], v32 offset:96
	s_waitcnt lgkmcnt(0)
	v_mfma_f32_32x32x16_bf16 v[16:31], v[36:39], v[76:79], v[16:31]
	ds_read_b128 v[36:39], v32 offset:4704
	v_lshlrev_b32_e32 v32, 2, v34
	v_sub_u32_e32 v32, v129, v32
	v_add_u32_e32 v35, 59, v32
	v_bfe_u32 v245, v195, 6, 2
	v_lshlrev_b32_e32 v245, 12, v245
	v_add_u32_e32 v245, 0x1e014, v245
	v_lshl_add_u32 v244, v35, 2, v245
	s_waitcnt lgkmcnt(0)
	v_mfma_f32_32x32x16_bf16 v[0:15], v[36:39], v[76:79], v[0:15]
	ds_read2_b32 v[196:197], v244 offset0:59 offset1:58
	ds_read2_b32 v[198:199], v244 offset0:57 offset1:56
	ds_read2_b32 v[200:201], v244 offset0:51 offset1:50
	ds_read2_b32 v[202:203], v244 offset0:49 offset1:48
	ds_read2_b32 v[204:205], v244 offset0:43 offset1:42
	ds_read2_b32 v[206:207], v244 offset0:41 offset1:40
	ds_read2_b32 v[208:209], v244 offset0:35 offset1:34
	ds_read2_b32 v[210:211], v244 offset0:33 offset1:32
	ds_read2_b32 v[212:213], v244 offset0:27 offset1:26
	ds_read2_b32 v[214:215], v244 offset0:25 offset1:24
	ds_read2_b32 v[216:217], v244 offset0:19 offset1:18
	ds_read2_b32 v[218:219], v244 offset0:17 offset1:16
	ds_read2_b32 v[236:237], v244 offset0:11 offset1:10
	ds_read2_b32 v[238:239], v244 offset0:9 offset1:8
	ds_read2_b32 v[240:241], v244 offset0:3 offset1:2
	s_waitcnt lgkmcnt(14)
	v_add_f32_e32 v134, v16, v196
	v_add_f32_e32 v63, v17, v197
	ds_read2_b32 v[242:243], v244 offset0:1 offset1:0
	s_waitcnt lgkmcnt(14)
	v_add_f32_e32 v133, v18, v198
	v_add_f32_e32 v58, v19, v199
	s_waitcnt lgkmcnt(13)
	v_add_f32_e32 v132, v20, v200
	v_add_f32_e32 v56, v21, v201
	s_waitcnt lgkmcnt(12)
	v_add_f32_e32 v62, v22, v202
	v_add_f32_e32 v54, v23, v203
	s_waitcnt lgkmcnt(11)
	v_add_f32_e32 v60, v24, v204
	v_add_f32_e32 v51, v25, v205
	s_waitcnt lgkmcnt(10)
	v_add_f32_e32 v57, v26, v206
	v_add_f32_e32 v48, v27, v207
	s_waitcnt lgkmcnt(9)
	v_add_f32_e32 v55, v28, v208
	v_add_f32_e32 v46, v29, v209
	s_waitcnt lgkmcnt(8)
	v_add_f32_e32 v52, v30, v210
	v_add_f32_e32 v43, v31, v211
	s_waitcnt lgkmcnt(7)
	v_add_f32_e32 v49, v0, v212
	v_add_f32_e32 v40, v1, v213
	s_waitcnt lgkmcnt(6)
	v_add_f32_e32 v47, v2, v214
	v_add_f32_e32 v38, v3, v215
	s_waitcnt lgkmcnt(5)
	v_add_f32_e32 v45, v4, v216
	v_add_f32_e32 v37, v5, v217
	s_waitcnt lgkmcnt(4)
	v_add_f32_e32 v42, v6, v218
	v_add_f32_e32 v36, v7, v219
	s_waitcnt lgkmcnt(3)
	v_add_f32_e32 v39, v8, v236
	v_add_f32_e32 v35, v9, v237
	s_waitcnt lgkmcnt(2)
	v_add_f32_e32 v44, v10, v238
	v_add_f32_e32 v41, v11, v239
	s_waitcnt lgkmcnt(1)
	v_add_f32_e32 v53, v12, v240
	v_add_f32_e32 v50, v13, v241
	s_waitcnt lgkmcnt(0)
	v_add_f32_e32 v61, v14, v242
	v_add_f32_e32 v59, v15, v243
	v_max3_f32 v0, v134, s93, v63
	v_max3_f32 v0, v0, v133, v58
	v_max3_f32 v0, v0, v132, v56
	v_max3_f32 v0, v0, v62, v54
	v_max3_f32 v0, v0, v60, v51
	v_max3_f32 v0, v0, v57, v48
	v_max3_f32 v0, v0, v55, v46
	v_max3_f32 v0, v0, v52, v43
	v_max3_f32 v0, v0, v49, v40
	v_max3_f32 v0, v0, v47, v38
	v_max3_f32 v0, v0, v45, v37
	v_max3_f32 v0, v0, v42, v36
	v_max3_f32 v0, v0, v39, v35
	v_max3_f32 v0, v0, v44, v41
	v_max3_f32 v0, v0, v53, v50
	v_max3_f32 v0, v0, v61, v59
	v_mov_b32_e32 v1, v0
	s_nop 1
	v_permlane32_swap_b32_e32 v1, v0
	s_waitcnt lgkmcnt(0)
	v_max_f32_e32 v0, v0, v1
	v_add_f32_e32 v1, 0x41000000, v126
	v_cmp_gt_f32_e32 vcc, v0, v1
	s_nop 1
	v_cndmask_b32_e32 v130, v126, v0, vcc
	v_sub_f32_e32 v0, v126, v130
	v_exp_f32_e32 v32, v0
	s_nop 0
	v_cmp_neq_f32_e32 vcc, 1.0, v32
	s_cbranch_vccz .LBB0_883
	v_pk_mul_f32 v[160:161], v[160:161], v[32:33] op_sel_hi:[1,0]
	v_pk_mul_f32 v[162:163], v[162:163], v[32:33] op_sel_hi:[1,0]
	v_pk_mul_f32 v[164:165], v[164:165], v[32:33] op_sel_hi:[1,0]
	v_pk_mul_f32 v[166:167], v[166:167], v[32:33] op_sel_hi:[1,0]
	v_pk_mul_f32 v[168:169], v[168:169], v[32:33] op_sel_hi:[1,0]
	v_pk_mul_f32 v[170:171], v[170:171], v[32:33] op_sel_hi:[1,0]
	v_pk_mul_f32 v[172:173], v[172:173], v[32:33] op_sel_hi:[1,0]
	v_pk_mul_f32 v[174:175], v[174:175], v[32:33] op_sel_hi:[1,0]
	v_pk_mul_f32 v[176:177], v[176:177], v[32:33] op_sel_hi:[1,0]
	v_pk_mul_f32 v[178:179], v[178:179], v[32:33] op_sel_hi:[1,0]
	v_pk_mul_f32 v[180:181], v[180:181], v[32:33] op_sel_hi:[1,0]
	v_pk_mul_f32 v[182:183], v[182:183], v[32:33] op_sel_hi:[1,0]
	v_pk_mul_f32 v[184:185], v[184:185], v[32:33] op_sel_hi:[1,0]
	v_pk_mul_f32 v[186:187], v[186:187], v[32:33] op_sel_hi:[1,0]
	v_pk_mul_f32 v[188:189], v[188:189], v[32:33] op_sel_hi:[1,0]
	v_pk_mul_f32 v[190:191], v[190:191], v[32:33] op_sel_hi:[1,0]
	s_cbranch_execnz .LBB0_879

; template <int NDT, int MODE, bool ALLON>
; DI void attn_tile(const bf16_t* Kl, int kst, const bf16_t* Vl, const bf16x8 (&q)[4], f32x16 (&O)[NDT], float& m, float& l,
;                   int kbase, int qp, int win, float cbias, const float* tab, bool lane_on) {
;     ...
;   for (int ks = 0; ks < 4; ++ks) {
;     const bf16x8 k0 = *(const bf16x8*)(Kl + lr * kst + ks * 16 + lh * 8);
;     const bf16x8 k1 = *(const bf16x8*)(Kl + (32 + lr) * kst + ks * 16 + lh * 8);
;     s[0] = MFMA32(k0, q[ks], s[0]);
;     s[1] = MFMA32(k1, q[ks], s[1]);
;   }
;   float alpha, psum = 0.f;
;   if (MODE == 0) {
;     float tmax = fmaxf(s[0][0], s[1][0]);
; #pragma unroll
;     for (int i = 1; i < 16; ++i) tmax = fmaxf(tmax, fmaxf(s[0][i], s[1][i]));
;     tmax = fmaxf(tmax, xor32(tmax)) + cbias;
;     if (!ALLON) tmax = lane_on ? tmax : -1e30f;
;     const float mn = fmaxf(m, tmax);
;     alpha = ex2(m - mn);
;     m = mn;
;     const float mc = (ALLON || lane_on) ? mn - cbias : 1e30f;
; #pragma unroll
;     for (int st = 0; st < 2; ++st)
; #pragma unroll
;       for (int i = 0; i < 16; ++i) { const float pe = ex2(s[st][i] - mc); psum += pe; s[st][i] = pe; }
;   } else {
;     float tmax = -1e30f;
; #pragma unroll
;     for (int st = 0; st < 2; ++st)
; #pragma unroll
;       for (int i = 0; i < 16; ++i) {
;         const int key = kbase + st * 32 + 8 * (i >> 2) + 4 * lh + (i & 3);
;         float v;
;         if (MODE == 1) {
;           const int dist = qp - key;
;           const bool ok = (ALLON || lane_on) && dist >= 0 && dist < win;
;           const int di = dist < 0 ? 0 : (dist > 128 ? 128 : dist);
;           v = ok ? s[st][i] + tab[di] : -1e30f;
;         } else {
;           v = (16 * key + 31 <= qp) ? s[st][i] : -1e30f;
;         }
;         s[st][i] = v;
;         tmax = fmaxf(tmax, v);
;       }
;     tmax = fmaxf(tmax, xor32(tmax));
;     const float mn = fmaxf(m, tmax);
;     alpha = ex2(m - mn);
;     m = mn;
; #pragma unroll
;     for (int st = 0; st < 2; ++st)
; #pragma unroll
;       for (int i = 0; i < 16; ++i) {
;         const float pe = s[st][i] > -5e29f ? ex2(s[st][i] - mn) : 0.f;
;         psum += pe;
;         s[st][i] = pe;
;       }
;   }
;   l = l * alpha + psum;
;   if (__ballot(alpha != 1.f)) {
; #pragma unroll
;     for (int dt = 0; dt < NDT; ++dt)
; #pragma unroll
;       for (int i = 0; i < 16; ++i) O[dt][i] *= alpha;
.LBB0_880:
	s_andn2_saveexec_b64 s[0:1], s[0:1]
	s_cbranch_execz .LBB0_806
	v_mov_b32_e32 v0, v195
	ds_read_b32 v134, v135 offset:37376
	s_nop 0
	v_and_b32_e32 v1, 31, v0
	v_lshrrev_b32_e32 v0, 2, v0
	v_mul_u32_u24_e32 v1, 0x48, v1
	v_and_b32_e32 v133, 8, v0
	v_lshlrev_b32_e32 v132, 1, v1
	v_lshlrev_b32_e32 v0, 1, v133
	v_add3_u32 v4, s25, v132, v0
	ds_read_b128 v[0:3], v4
	s_waitcnt lgkmcnt(0)
	v_mfma_f32_32x32x16_bf16 v[48:63], v[0:3], v[64:67], 0
	ds_read_b128 v[0:3], v4 offset:4608
	s_waitcnt lgkmcnt(0)
	v_mfma_f32_32x32x16_bf16 v[32:47], v[0:3], v[64:67], 0
	ds_read_b128 v[0:3], v4 offset:32
	s_waitcnt lgkmcnt(0)
	v_mfma_f32_32x32x16_bf16 v[48:63], v[0:3], v[68:71], v[48:63]
	ds_read_b128 v[0:3], v4 offset:4640
	s_waitcnt lgkmcnt(0)
	v_mfma_f32_32x32x16_bf16 v[32:47], v[0:3], v[68:71], v[32:47]
	ds_read_b128 v[0:3], v4 offset:64
	s_waitcnt lgkmcnt(0)
	v_mfma_f32_32x32x16_bf16 v[48:63], v[0:3], v[72:75], v[48:63]
	ds_read_b128 v[0:3], v4 offset:4672
	s_waitcnt lgkmcnt(0)
	v_mfma_f32_32x32x16_bf16 v[32:47], v[0:3], v[72:75], v[32:47]
	ds_read_b128 v[0:3], v4 offset:4704
	s_waitcnt lgkmcnt(0)
	v_mfma_f32_32x32x16_bf16 v[32:47], v[0:3], v[76:79], v[32:47]
	ds_read_b128 v[0:3], v4 offset:96
	s_waitcnt lgkmcnt(0)
	v_mfma_f32_32x32x16_bf16 v[48:63], v[0:3], v[76:79], v[48:63]
	s_nop 8
	v_max3_f32 v0, v32, v33, v34
	v_max3_f32 v0, v0, v35, v36
	v_max3_f32 v0, v0, v37, v38
	v_max3_f32 v0, v0, v39, v40
	v_max3_f32 v0, v0, v41, v42
	v_max3_f32 v0, v0, v43, v44
	v_max3_f32 v0, v0, v45, v46
	v_max_f32_e32 v0, v0, v47
	v_max3_f32 v1, v48, v49, v50
	v_max3_f32 v1, v1, v51, v52
	v_max3_f32 v1, v1, v53, v54
	v_max3_f32 v1, v1, v55, v56
	v_max3_f32 v1, v1, v57, v58
	v_max3_f32 v1, v1, v59, v60
	v_max3_f32 v1, v1, v61, v62
	v_max_f32_e32 v1, v1, v63
	v_max_f32_e32 v0, v0, v1
	v_mov_b32_e32 v1, v0
	s_nop 1
	v_permlane32_swap_b32_e32 v1, v0
	s_waitcnt lgkmcnt(0)
	v_max_f32_e32 v0, v0, v1
	v_add_f32_e32 v0, v134, v0
	v_add_f32_e32 v1, 0x41000000, v126
	v_cmp_gt_f32_e32 vcc, v0, v1
	s_nop 1
	v_cndmask_b32_e32 v130, v126, v0, vcc
	v_sub_f32_e32 v0, v126, v130
	v_exp_f32_e32 v126, v0
	s_nop 0
	v_cmp_neq_f32_e32 vcc, 1.0, v126
	s_cbranch_vccz .LBB0_884
	v_pk_mul_f32 v[160:161], v[160:161], v[126:127] op_sel_hi:[1,0]
	v_pk_mul_f32 v[162:163], v[162:163], v[126:127] op_sel_hi:[1,0]
	v_pk_mul_f32 v[164:165], v[164:165], v[126:127] op_sel_hi:[1,0]
	v_pk_mul_f32 v[166:167], v[166:167], v[126:127] op_sel_hi:[1,0]
	v_pk_mul_f32 v[168:169], v[168:169], v[126:127] op_sel_hi:[1,0]
	v_pk_mul_f32 v[170:171], v[170:171], v[126:127] op_sel_hi:[1,0]
	v_pk_mul_f32 v[172:173], v[172:173], v[126:127] op_sel_hi:[1,0]
	v_pk_mul_f32 v[174:175], v[174:175], v[126:127] op_sel_hi:[1,0]
	v_pk_mul_f32 v[176:177], v[176:177], v[126:127] op_sel_hi:[1,0]
	v_pk_mul_f32 v[178:179], v[178:179], v[126:127] op_sel_hi:[1,0]
	v_pk_mul_f32 v[180:181], v[180:181], v[126:127] op_sel_hi:[1,0]
	v_pk_mul_f32 v[182:183], v[182:183], v[126:127] op_sel_hi:[1,0]
	v_pk_mul_f32 v[184:185], v[184:185], v[126:127] op_sel_hi:[1,0]
	v_pk_mul_f32 v[186:187], v[186:187], v[126:127] op_sel_hi:[1,0]
	v_pk_mul_f32 v[188:189], v[188:189], v[126:127] op_sel_hi:[1,0]
	v_pk_mul_f32 v[190:191], v[190:191], v[126:127] op_sel_hi:[1,0]
	s_cbranch_execnz .LBB0_805
	s_branch .LBB0_804

; template <int NDT, int MODE, bool ALLON>
; DI void attn_tile(const bf16_t* Kl, int kst, const bf16_t* Vl, const bf16x8 (&q)[4], f32x16 (&O)[NDT], float& m, float& l,
;                   int kbase, int qp, int win, float cbias, const float* tab, bool lane_on) {
;     ...
;   for (int ks = 0; ks < 4; ++ks) {
;     const bf16x8 k0 = *(const bf16x8*)(Kl + lr * kst + ks * 16 + lh * 8);
;     const bf16x8 k1 = *(const bf16x8*)(Kl + (32 + lr) * kst + ks * 16 + lh * 8);
;     s[0] = MFMA32(k0, q[ks], s[0]);
;     s[1] = MFMA32(k1, q[ks], s[1]);
;   }
;   float alpha, psum = 0.f;
;   if (MODE == 0) {
;     float tmax = fmaxf(s[0][0], s[1][0]);
; #pragma unroll
;     for (int i = 1; i < 16; ++i) tmax = fmaxf(tmax, fmaxf(s[0][i], s[1][i]));
;     tmax = fmaxf(tmax, xor32(tmax)) + cbias;
;     if (!ALLON) tmax = lane_on ? tmax : -1e30f;
;     const float mn = fmaxf(m, tmax);
;     alpha = ex2(m - mn);
;     m = mn;
;     const float mc = (ALLON || lane_on) ? mn - cbias : 1e30f;
; #pragma unroll
;     for (int st = 0; st < 2; ++st)
; #pragma unroll
;       for (int i = 0; i < 16; ++i) { const float pe = ex2(s[st][i] - mc); psum += pe; s[st][i] = pe; }
;   } else {
;     float tmax = -1e30f;
; #pragma unroll
;     for (int st = 0; st < 2; ++st)
; #pragma unroll
;       for (int i = 0; i < 16; ++i) {
;         const int key = kbase + st * 32 + 8 * (i >> 2) + 4 * lh + (i & 3);
;         float v;
;         if (MODE == 1) {
;           const int dist = qp - key;
;           const bool ok = (ALLON || lane_on) && dist >= 0 && dist < win;
;           const int di = dist < 0 ? 0 : (dist > 128 ? 128 : dist);
;           v = ok ? s[st][i] + tab[di] : -1e30f;
;         } else {
;           v = (16 * key + 31 <= qp) ? s[st][i] : -1e30f;
;         }
;         s[st][i] = v;
;         tmax = fmaxf(tmax, v);
;       }
;     tmax = fmaxf(tmax, xor32(tmax));
;     const float mn = fmaxf(m, tmax);
;     alpha = ex2(m - mn);
;     m = mn;
; #pragma unroll
;     for (int st = 0; st < 2; ++st)
; #pragma unroll
;       for (int i = 0; i < 16; ++i) {
;         const float pe = s[st][i] > -5e29f ? ex2(s[st][i] - mn) : 0.f;
;         psum += pe;
;         s[st][i] = pe;
;       }
;   }
;   l = l * alpha + psum;
;   if (__ballot(alpha != 1.f)) {
; #pragma unroll
;     for (int dt = 0; dt < NDT; ++dt)
; #pragma unroll
;       for (int i = 0; i < 16; ++i) O[dt][i] *= alpha;
.LBB0_902:
	v_cmp_le_i32_e32 vcc, s6, v94
	v_cmp_ge_i32_e64 s[0:1], s6, v93
	s_and_b64 s[28:29], vcc, s[0:1]
	s_waitcnt lgkmcnt(0)
	s_barrier
	s_and_saveexec_b64 s[0:1], s[28:29]
	s_cbranch_execz .LBB0_899
	v_mov_b32_e32 v0, v195
	v_mov_b32_e32 v131, 0xf149f2ca
	v_and_b32_e32 v1, 31, v0
	v_bfe_u32 v108, v0, 5, 1
	v_mul_u32_u24_e32 v0, 0x48, v1
	v_lshlrev_b32_e32 v99, 1, v0
	v_lshlrev_b32_e32 v109, 4, v108
	v_add3_u32 v110, s31, v99, v109
	ds_read_b128 v[0:3], v110 offset:4608
	ds_read_b128 v[4:7], v110
	ds_read_b128 v[100:103], v110 offset:32
	ds_read_b128 v[104:107], v110 offset:4640
	s_waitcnt lgkmcnt(2)
	v_mfma_f32_32x32x16_bf16 v[16:31], v[4:7], v[32:35], 0
	v_mov_b32_e32 v133, 0xf149f2ca
	v_mfma_f32_32x32x16_bf16 v[0:15], v[0:3], v[32:35], 0
	s_waitcnt lgkmcnt(1)
	v_mfma_f32_32x32x16_bf16 v[16:31], v[100:103], v[36:39], v[16:31]
	s_waitcnt lgkmcnt(0)
	v_mfma_f32_32x32x16_bf16 v[0:15], v[104:107], v[36:39], v[0:15]
	ds_read_b128 v[100:103], v110 offset:64
	ds_read_b128 v[104:107], v110 offset:4672
	s_waitcnt lgkmcnt(1)
	v_mfma_f32_32x32x16_bf16 v[16:31], v[100:103], v[40:43], v[16:31]
	s_waitcnt lgkmcnt(0)
	v_mfma_f32_32x32x16_bf16 v[0:15], v[104:107], v[40:43], v[0:15]
	ds_read_b128 v[100:103], v110 offset:96
	ds_read_b128 v[104:107], v110 offset:4704
	s_waitcnt lgkmcnt(1)
	v_mfma_f32_32x32x16_bf16 v[16:31], v[100:103], v[44:47], v[16:31]
	v_lshlrev_b32_e32 v100, 2, v108
	v_sub_u32_e32 v134, v96, v100
	v_add_u32_e32 v101, 59, v134
	v_bfe_u32 v245, v195, 6, 2
	v_lshlrev_b32_e32 v245, 12, v245
	v_add_u32_e32 v245, 0x1e014, v245
	v_lshl_add_u32 v244, v101, 2, v245
	v_sub_u32_e32 v101, v97, v109
	s_waitcnt lgkmcnt(0)
	v_mfma_f32_32x32x16_bf16 v[0:15], v[104:107], v[44:47], v[0:15]
	ds_read2_b32 v[196:197], v244 offset0:59 offset1:58
	ds_read2_b32 v[198:199], v244 offset0:57 offset1:56
	ds_read2_b32 v[200:201], v244 offset0:51 offset1:50
	ds_read2_b32 v[202:203], v244 offset0:49 offset1:48
	ds_read2_b32 v[204:205], v244 offset0:43 offset1:42
	ds_read2_b32 v[206:207], v244 offset0:41 offset1:40
	ds_read2_b32 v[208:209], v244 offset0:35 offset1:34
	ds_read2_b32 v[210:211], v244 offset0:33 offset1:32
	ds_read2_b32 v[212:213], v244 offset0:27 offset1:26
	ds_read2_b32 v[214:215], v244 offset0:25 offset1:24
	ds_read2_b32 v[216:217], v244 offset0:19 offset1:18
	ds_read2_b32 v[218:219], v244 offset0:17 offset1:16
	ds_read2_b32 v[236:237], v244 offset0:11 offset1:10
	ds_read2_b32 v[238:239], v244 offset0:9 offset1:8
	ds_read2_b32 v[240:241], v244 offset0:3 offset1:2
	s_waitcnt lgkmcnt(14)
	v_add_f32_e32 v133, v16, v196
	v_add_f32_e32 v131, v17, v197
	ds_read2_b32 v[242:243], v244 offset0:1 offset1:0
	s_waitcnt lgkmcnt(14)
	v_add_f32_e32 v132, v18, v198
	v_add_f32_e32 v128, v19, v199
	s_waitcnt lgkmcnt(13)
	v_add_f32_e32 v130, v20, v200
	v_add_f32_e32 v126, v21, v201
	s_waitcnt lgkmcnt(12)
	v_add_f32_e32 v129, v22, v202
	v_add_f32_e32 v124, v23, v203
	s_waitcnt lgkmcnt(11)
	v_add_f32_e32 v127, v24, v204
	v_add_f32_e32 v122, v25, v205
	s_waitcnt lgkmcnt(10)
	v_add_f32_e32 v125, v26, v206
	v_add_f32_e32 v120, v27, v207
	s_waitcnt lgkmcnt(9)
	v_add_f32_e32 v123, v28, v208
	v_add_f32_e32 v116, v29, v209
	s_waitcnt lgkmcnt(8)
	v_add_f32_e32 v121, v30, v210
	v_add_f32_e32 v114, v31, v211
	s_waitcnt lgkmcnt(7)
	v_add_f32_e32 v118, v0, v212
	v_add_f32_e32 v110, v1, v213
	s_waitcnt lgkmcnt(6)
	v_add_f32_e32 v115, v2, v214
	v_add_f32_e32 v108, v3, v215
	s_waitcnt lgkmcnt(5)
	v_add_f32_e32 v112, v4, v216
	v_add_f32_e32 v104, v5, v217
	s_waitcnt lgkmcnt(4)
	v_add_f32_e32 v109, v6, v218
	v_add_f32_e32 v103, v7, v219
	s_waitcnt lgkmcnt(3)
	v_add_f32_e32 v105, v8, v236
	v_add_f32_e32 v102, v9, v237
	s_waitcnt lgkmcnt(2)
	v_add_f32_e32 v107, v10, v238
	v_add_f32_e32 v106, v11, v239
	s_waitcnt lgkmcnt(1)
	v_add_f32_e32 v113, v12, v240
	v_add_f32_e32 v111, v13, v241
	s_waitcnt lgkmcnt(0)
	v_add_f32_e32 v119, v14, v242
	v_add_f32_e32 v117, v15, v243
	v_max3_f32 v0, v133, s93, v131
	v_max3_f32 v0, v0, v132, v128
	v_max3_f32 v0, v0, v130, v126
	v_max3_f32 v0, v0, v129, v124
	v_max3_f32 v0, v0, v127, v122
	v_max3_f32 v0, v0, v125, v120
	v_max3_f32 v0, v0, v123, v116
	v_max3_f32 v0, v0, v121, v114
	v_max3_f32 v0, v0, v118, v110
	v_max3_f32 v0, v0, v115, v108
	v_max3_f32 v0, v0, v112, v104
	v_max3_f32 v0, v0, v109, v103
	v_and_b32_e32 v2, 64, v231
	v_max3_f32 v0, v0, v105, v102
	v_xor_b32_e32 v1, 32, v231
	v_add_u32_e32 v2, 64, v2
	v_max3_f32 v0, v0, v107, v106
	v_cmp_lt_i32_e32 vcc, v1, v2
	v_max3_f32 v0, v0, v113, v111
	v_max3_f32 v0, v0, v119, v117
	v_cndmask_b32_e32 v1, v231, v1, vcc
	v_lshlrev_b32_e32 v1, 2, v1
	v_mov_b32_e32 v1, v0
	s_nop 1
	v_permlane32_swap_b32_e32 v1, v0
	s_waitcnt lgkmcnt(0)
	v_max_f32_e32 v0, v0, v1
	v_add_f32_e32 v1, 0x41000000, v90
	v_cmp_gt_f32_e32 vcc, v0, v1
	s_nop 1
	v_cndmask_b32_e32 v101, v90, v0, vcc
	v_sub_f32_e32 v0, v90, v101
	v_exp_f32_e32 v90, v0
	s_nop 0
	v_cmp_neq_f32_e32 vcc, 1.0, v90
	s_cbranch_vccz .LBB0_969
	v_pk_mul_f32 v[0:1], v[86:87], v[90:91] op_sel_hi:[1,0]
	v_pk_mul_f32 v[2:3], v[88:89], v[90:91] op_sel_hi:[1,0]
	v_pk_mul_f32 v[4:5], v[84:85], v[90:91] op_sel_hi:[1,0]
	v_pk_mul_f32 v[6:7], v[82:83], v[90:91] op_sel_hi:[1,0]
	v_pk_mul_f32 v[8:9], v[80:81], v[90:91] op_sel_hi:[1,0]
	v_pk_mul_f32 v[10:11], v[76:77], v[90:91] op_sel_hi:[1,0]
	v_pk_mul_f32 v[12:13], v[72:73], v[90:91] op_sel_hi:[1,0]
	v_pk_mul_f32 v[14:15], v[68:69], v[90:91] op_sel_hi:[1,0]
	v_pk_mul_f32 v[16:17], v[78:79], v[90:91] op_sel_hi:[1,0]
	v_pk_mul_f32 v[18:19], v[74:75], v[90:91] op_sel_hi:[1,0]
	v_pk_mul_f32 v[20:21], v[70:71], v[90:91] op_sel_hi:[1,0]
	v_pk_mul_f32 v[22:23], v[66:67], v[90:91] op_sel_hi:[1,0]
	v_pk_mul_f32 v[24:25], v[64:65], v[90:91] op_sel_hi:[1,0]
	v_pk_mul_f32 v[26:27], v[62:63], v[90:91] op_sel_hi:[1,0]
	v_pk_mul_f32 v[28:29], v[60:61], v[90:91] op_sel_hi:[1,0]
	v_pk_mul_f32 v[30:31], v[58:59], v[90:91] op_sel_hi:[1,0]
	s_cbranch_execnz .LBB0_898
	s_branch .LBB0_897

; template <int NDT, int MODE, bool ALLON>
; DI void attn_tile(const bf16_t* Kl, int kst, const bf16_t* Vl, const bf16x8 (&q)[4], f32x16 (&O)[NDT], float& m, float& l,
;                   int kbase, int qp, int win, float cbias, const float* tab, bool lane_on) {
;     ...
;   for (int ks = 0; ks < 4; ++ks) {
;     const bf16x8 k0 = *(const bf16x8*)(Kl + lr * kst + ks * 16 + lh * 8);
;     const bf16x8 k1 = *(const bf16x8*)(Kl + (32 + lr) * kst + ks * 16 + lh * 8);
;     s[0] = MFMA32(k0, q[ks], s[0]);
;     s[1] = MFMA32(k1, q[ks], s[1]);
;   }
;   float alpha, psum = 0.f;
;   if (MODE == 0) {
;     float tmax = fmaxf(s[0][0], s[1][0]);
; #pragma unroll
;     for (int i = 1; i < 16; ++i) tmax = fmaxf(tmax, fmaxf(s[0][i], s[1][i]));
;     tmax = fmaxf(tmax, xor32(tmax)) + cbias;
;     if (!ALLON) tmax = lane_on ? tmax : -1e30f;
;     const float mn = fmaxf(m, tmax);
;     alpha = ex2(m - mn);
;     m = mn;
;     const float mc = (ALLON || lane_on) ? mn - cbias : 1e30f;
; #pragma unroll
;     for (int st = 0; st < 2; ++st)
; #pragma unroll
;       for (int i = 0; i < 16; ++i) { const float pe = ex2(s[st][i] - mc); psum += pe; s[st][i] = pe; }
;   } else {
;     float tmax = -1e30f;
; #pragma unroll
;     for (int st = 0; st < 2; ++st)
; #pragma unroll
;       for (int i = 0; i < 16; ++i) {
;         const int key = kbase + st * 32 + 8 * (i >> 2) + 4 * lh + (i & 3);
;         float v;
;         if (MODE == 1) {
;           const int dist = qp - key;
;           const bool ok = (ALLON || lane_on) && dist >= 0 && dist < win;
;           const int di = dist < 0 ? 0 : (dist > 128 ? 128 : dist);
;           v = ok ? s[st][i] + tab[di] : -1e30f;
;         } else {
;           v = (16 * key + 31 <= qp) ? s[st][i] : -1e30f;
;         }
;         s[st][i] = v;
;         tmax = fmaxf(tmax, v);
;       }
;     tmax = fmaxf(tmax, xor32(tmax));
;     const float mn = fmaxf(m, tmax);
;     alpha = ex2(m - mn);
;     m = mn;
; #pragma unroll
;     for (int st = 0; st < 2; ++st)
; #pragma unroll
;       for (int i = 0; i < 16; ++i) {
;         const float pe = s[st][i] > -5e29f ? ex2(s[st][i] - mn) : 0.f;
;         psum += pe;
;         s[st][i] = pe;
;       }
;   }
;   l = l * alpha + psum;
;   if (__ballot(alpha != 1.f)) {
; #pragma unroll
;     for (int dt = 0; dt < NDT; ++dt)
; #pragma unroll
;       for (int i = 0; i < 16; ++i) O[dt][i] *= alpha;
.LattnA_cb_ok:
	v_add_u32_e32 v150, v69, v178
	ds_read_b128 v[68:71], v150
	ds_read_b128 v[156:159], v150 offset:32
	s_waitcnt lgkmcnt(1)
	v_mfma_f32_32x32x16_bf16 v[80:95], v[68:71], v[64:67], v[160:175]
	ds_read_b128 v[68:71], v150 offset:8704
	s_waitcnt lgkmcnt(1)
	v_mfma_f32_32x32x16_bf16 v[80:95], v[156:159], v[120:123], v[80:95]
	ds_read_b128 v[156:159], v150 offset:8736
	s_waitcnt lgkmcnt(1)
	v_mfma_f32_32x32x16_bf16 v[64:79], v[68:71], v[64:67], v[160:175]
	s_waitcnt lgkmcnt(0)
	v_mfma_f32_32x32x16_bf16 v[64:79], v[156:159], v[120:123], v[64:79]
	ds_read_b128 v[120:123], v150 offset:64
	s_waitcnt lgkmcnt(0)
	v_mfma_f32_32x32x16_bf16 v[80:95], v[120:123], v[116:119], v[80:95]
	ds_read_b128 v[120:123], v150 offset:8768
	s_waitcnt lgkmcnt(0)
	v_mfma_f32_32x32x16_bf16 v[64:79], v[120:123], v[116:119], v[64:79]
	ds_read_b128 v[116:119], v150 offset:8800
	s_waitcnt lgkmcnt(0)
	v_mfma_f32_32x32x16_bf16 v[64:79], v[116:119], v[112:115], v[64:79]
	ds_read_b128 v[116:119], v150 offset:96
	s_waitcnt lgkmcnt(0)
	v_mfma_f32_32x32x16_bf16 v[80:95], v[116:119], v[112:115], v[80:95]
	s_nop 8
	v_max3_f32 v112, v64, v65, v66
	v_max3_f32 v112, v112, v67, v68
	v_max3_f32 v112, v112, v69, v70
	v_max3_f32 v112, v112, v71, v72
	v_max3_f32 v112, v112, v73, v74
	v_max3_f32 v112, v112, v75, v76
	v_max3_f32 v112, v112, v77, v78
	v_max_f32_e32 v112, v112, v79
	v_max3_f32 v113, v80, v81, v82
	v_max3_f32 v113, v113, v83, v84
	v_max3_f32 v113, v113, v85, v86
	v_max3_f32 v113, v113, v87, v88
	v_max3_f32 v113, v113, v89, v90
	v_max3_f32 v113, v113, v91, v92
	v_max3_f32 v113, v113, v93, v94
	v_max_f32_e32 v113, v113, v95
	v_max_f32_e32 v112, v112, v113
	v_mov_b32_e32 v113, v112
	s_nop 1
	v_permlane32_swap_b32_e32 v113, v112
	s_waitcnt lgkmcnt(0)
	v_max_f32_e32 v112, v112, v113
	v_cmp_lt_f32_e32 vcc, 0x41000000, v112
	v_cmp_eq_f32_e64 s[46:47], v154, v232
	s_nop 1
	s_or_b64 s[48:49], vcc, s[46:47]
	s_cbranch_scc0 .LattnA_fast
	v_add_f32_e32 v80, v177, v80
	v_add_f32_e32 v81, v177, v81
	v_add_f32_e32 v82, v177, v82
	v_add_f32_e32 v83, v177, v83
	v_add_f32_e32 v84, v177, v84
	v_add_f32_e32 v85, v177, v85
	v_add_f32_e32 v86, v177, v86
	v_add_f32_e32 v87, v177, v87
	v_add_f32_e32 v88, v177, v88
	v_add_f32_e32 v89, v177, v89
	v_add_f32_e32 v90, v177, v90
	v_add_f32_e32 v91, v177, v91
	v_add_f32_e32 v92, v177, v92
	v_add_f32_e32 v93, v177, v93
	v_add_f32_e32 v94, v177, v94
	v_add_f32_e32 v95, v177, v95
	v_add_f32_e32 v64, v177, v64
	v_add_f32_e32 v65, v177, v65
	v_add_f32_e32 v66, v177, v66
	v_add_f32_e32 v67, v177, v67
	v_add_f32_e32 v68, v177, v68
	v_add_f32_e32 v69, v177, v69
	v_add_f32_e32 v70, v177, v70
	v_add_f32_e32 v71, v177, v71
	v_add_f32_e32 v72, v177, v72
	v_add_f32_e32 v73, v177, v73
	v_add_f32_e32 v74, v177, v74
	v_add_f32_e32 v75, v177, v75
	v_add_f32_e32 v76, v177, v76
	v_add_f32_e32 v77, v177, v77
	v_add_f32_e32 v78, v177, v78
	v_add_f32_e32 v79, v177, v79
	v_add_f32_e32 v112, v177, v112
	v_add_f32_e32 v112, v155, v112
	v_add_f32_e32 v113, 0x41000000, v154
	v_cmp_gt_f32_e32 vcc, v112, v113
	s_nop 1
	v_cndmask_b32_e32 v150, v154, v112, vcc
	v_sub_f32_e32 v112, v154, v150
	v_exp_f32_e32 v112, v112
	s_nop 0
	v_cmp_neq_f32_e32 vcc, 1.0, v112
	s_cbranch_vccz .LBB0_984
	v_pk_mul_f32 v[62:63], v[62:63], v[112:113] op_sel_hi:[1,0]
	v_pk_mul_f32 v[60:61], v[60:61], v[112:113] op_sel_hi:[1,0]
	v_pk_mul_f32 v[58:59], v[58:59], v[112:113] op_sel_hi:[1,0]
	v_pk_mul_f32 v[56:57], v[56:57], v[112:113] op_sel_hi:[1,0]
	v_pk_mul_f32 v[54:55], v[54:55], v[112:113] op_sel_hi:[1,0]
	v_pk_mul_f32 v[52:53], v[52:53], v[112:113] op_sel_hi:[1,0]
	v_pk_mul_f32 v[50:51], v[50:51], v[112:113] op_sel_hi:[1,0]
	v_pk_mul_f32 v[48:49], v[48:49], v[112:113] op_sel_hi:[1,0]
	v_pk_mul_f32 v[46:47], v[46:47], v[112:113] op_sel_hi:[1,0]
	v_pk_mul_f32 v[44:45], v[44:45], v[112:113] op_sel_hi:[1,0]
	v_pk_mul_f32 v[42:43], v[42:43], v[112:113] op_sel_hi:[1,0]
	v_pk_mul_f32 v[40:41], v[40:41], v[112:113] op_sel_hi:[1,0]
	v_pk_mul_f32 v[38:39], v[38:39], v[112:113] op_sel_hi:[1,0]
	v_pk_mul_f32 v[36:37], v[36:37], v[112:113] op_sel_hi:[1,0]
	v_pk_mul_f32 v[34:35], v[34:35], v[112:113] op_sel_hi:[1,0]
	v_pk_mul_f32 v[32:33], v[32:33], v[112:113] op_sel_hi:[1,0]
	v_pk_mul_f32 v[30:31], v[30:31], v[112:113] op_sel_hi:[1,0]
	v_pk_mul_f32 v[28:29], v[28:29], v[112:113] op_sel_hi:[1,0]
	v_pk_mul_f32 v[26:27], v[26:27], v[112:113] op_sel_hi:[1,0]
	v_pk_mul_f32 v[24:25], v[24:25], v[112:113] op_sel_hi:[1,0]
	v_pk_mul_f32 v[22:23], v[22:23], v[112:113] op_sel_hi:[1,0]
	v_pk_mul_f32 v[20:21], v[20:21], v[112:113] op_sel_hi:[1,0]
	v_pk_mul_f32 v[18:19], v[18:19], v[112:113] op_sel_hi:[1,0]
	v_pk_mul_f32 v[16:17], v[16:17], v[112:113] op_sel_hi:[1,0]
	v_pk_mul_f32 v[14:15], v[14:15], v[112:113] op_sel_hi:[1,0]
	v_pk_mul_f32 v[12:13], v[12:13], v[112:113] op_sel_hi:[1,0]
	v_pk_mul_f32 v[10:11], v[10:11], v[112:113] op_sel_hi:[1,0]
	v_pk_mul_f32 v[8:9], v[8:9], v[112:113] op_sel_hi:[1,0]
	v_pk_mul_f32 v[6:7], v[6:7], v[112:113] op_sel_hi:[1,0]
	v_pk_mul_f32 v[4:5], v[4:5], v[112:113] op_sel_hi:[1,0]
	v_pk_mul_f32 v[2:3], v[2:3], v[112:113] op_sel_hi:[1,0]
	v_pk_mul_f32 v[0:1], v[0:1], v[112:113] op_sel_hi:[1,0]

; template <int NDT, int MODE, bool ALLON>
; DI void attn_tile(const bf16_t* Kl, int kst, const bf16_t* Vl, const bf16x8 (&q)[4], f32x16 (&O)[NDT], float& m, float& l,
;                   int kbase, int qp, int win, float cbias, const float* tab, bool lane_on) {
;     ...
;   for (int ks = 0; ks < 4; ++ks) {
;     const bf16x8 k0 = *(const bf16x8*)(Kl + lr * kst + ks * 16 + lh * 8);
;     const bf16x8 k1 = *(const bf16x8*)(Kl + (32 + lr) * kst + ks * 16 + lh * 8);
;     s[0] = MFMA32(k0, q[ks], s[0]);
;     s[1] = MFMA32(k1, q[ks], s[1]);
;   }
;   float alpha, psum = 0.f;
;   if (MODE == 0) {
;     float tmax = fmaxf(s[0][0], s[1][0]);
; #pragma unroll
;     for (int i = 1; i < 16; ++i) tmax = fmaxf(tmax, fmaxf(s[0][i], s[1][i]));
;     tmax = fmaxf(tmax, xor32(tmax)) + cbias;
;     if (!ALLON) tmax = lane_on ? tmax : -1e30f;
;     const float mn = fmaxf(m, tmax);
;     alpha = ex2(m - mn);
;     m = mn;
;     const float mc = (ALLON || lane_on) ? mn - cbias : 1e30f;
; #pragma unroll
;     for (int st = 0; st < 2; ++st)
; #pragma unroll
;       for (int i = 0; i < 16; ++i) { const float pe = ex2(s[st][i] - mc); psum += pe; s[st][i] = pe; }
;   } else {
;     float tmax = -1e30f;
; #pragma unroll
;     for (int st = 0; st < 2; ++st)
; #pragma unroll
;       for (int i = 0; i < 16; ++i) {
;         const int key = kbase + st * 32 + 8 * (i >> 2) + 4 * lh + (i & 3);
;         float v;
;         if (MODE == 1) {
;           const int dist = qp - key;
;           const bool ok = (ALLON || lane_on) && dist >= 0 && dist < win;
;           const int di = dist < 0 ? 0 : (dist > 128 ? 128 : dist);
;           v = ok ? s[st][i] + tab[di] : -1e30f;
;         } else {
;           v = (16 * key + 31 <= qp) ? s[st][i] : -1e30f;
;         }
;         s[st][i] = v;
;         tmax = fmaxf(tmax, v);
;       }
;     tmax = fmaxf(tmax, xor32(tmax));
;     const float mn = fmaxf(m, tmax);
;     alpha = ex2(m - mn);
;     m = mn;
; #pragma unroll
;     for (int st = 0; st < 2; ++st)
; #pragma unroll
;       for (int i = 0; i < 16; ++i) {
;         const float pe = s[st][i] > -5e29f ? ex2(s[st][i] - mn) : 0.f;
;         psum += pe;
;         s[st][i] = pe;
;       }
;   }
;   l = l * alpha + psum;
;   if (__ballot(alpha != 1.f)) {
; #pragma unroll
;     for (int dt = 0; dt < NDT; ++dt)
; #pragma unroll
;       for (int i = 0; i < 16; ++i) O[dt][i] *= alpha;
.LBB0_985:
	s_andn2_saveexec_b64 s[2:3], s[2:3]
	s_cbranch_execz .LBB0_976
	v_mov_b32_e32 v68, v195
	s_nop 0
	v_and_b32_e32 v152, 31, v68
	v_bfe_u32 v153, v68, 5, 1
	v_mul_u32_u24_e32 v68, 0x110, v152
	v_lshlrev_b32_e32 v70, 4, v153
	v_add3_u32 v150, v69, v68, v70
	ds_read_b128 v[68:71], v150
	ds_read_b128 v[156:159], v150 offset:32
	s_waitcnt lgkmcnt(1)
	v_mfma_f32_32x32x16_bf16 v[80:95], v[68:71], v[64:67], 0
	ds_read_b128 v[68:71], v150 offset:8704
	s_waitcnt lgkmcnt(1)
	v_mfma_f32_32x32x16_bf16 v[80:95], v[156:159], v[120:123], v[80:95]
	ds_read_b128 v[156:159], v150 offset:8736
	s_waitcnt lgkmcnt(1)
	v_mfma_f32_32x32x16_bf16 v[64:79], v[68:71], v[64:67], 0
	s_waitcnt lgkmcnt(0)
	v_mfma_f32_32x32x16_bf16 v[64:79], v[156:159], v[120:123], v[64:79]
	ds_read_b128 v[120:123], v150 offset:64
	ds_read_b128 v[156:159], v150 offset:8800
	s_waitcnt lgkmcnt(1)
	v_mfma_f32_32x32x16_bf16 v[80:95], v[120:123], v[116:119], v[80:95]
	ds_read_b128 v[120:123], v150 offset:8768
	s_waitcnt lgkmcnt(0)
	v_mfma_f32_32x32x16_bf16 v[64:79], v[120:123], v[116:119], v[64:79]
	ds_read_b128 v[116:119], v150 offset:96
	v_mov_b32_e32 v120, 0xf149f2ca
	s_waitcnt lgkmcnt(0)
	v_mfma_f32_32x32x16_bf16 v[80:95], v[116:119], v[112:115], v[80:95]
	v_lshlrev_b32_e32 v116, 2, v153
	v_sub_u32_e32 v123, v127, v116
	v_add_u32_e32 v117, 59, v123
	v_mov_b32_e32 v245, 0x1e014
	v_lshl_add_u32 v244, v117, 2, v245
	v_mov_b32_e32 v116, 0xf149f2ca
	v_mfma_f32_32x32x16_bf16 v[64:79], v[156:159], v[112:115], v[64:79]
	ds_read2_b32 v[196:197], v244 offset0:59 offset1:58
	ds_read2_b32 v[198:199], v244 offset0:57 offset1:56
	ds_read2_b32 v[200:201], v244 offset0:51 offset1:50
	ds_read2_b32 v[202:203], v244 offset0:49 offset1:48
	ds_read2_b32 v[204:205], v244 offset0:43 offset1:42
	ds_read2_b32 v[206:207], v244 offset0:41 offset1:40
	ds_read2_b32 v[208:209], v244 offset0:35 offset1:34
	ds_read2_b32 v[210:211], v244 offset0:33 offset1:32
	ds_read2_b32 v[212:213], v244 offset0:27 offset1:26
	ds_read2_b32 v[214:215], v244 offset0:25 offset1:24
	ds_read2_b32 v[216:217], v244 offset0:19 offset1:18
	ds_read2_b32 v[218:219], v244 offset0:17 offset1:16
	ds_read2_b32 v[236:237], v244 offset0:11 offset1:10
	ds_read2_b32 v[238:239], v244 offset0:9 offset1:8
	ds_read2_b32 v[240:241], v244 offset0:3 offset1:2
	s_waitcnt lgkmcnt(14)
	v_add_f32_e32 v120, v80, v196
	v_add_f32_e32 v116, v81, v197
	ds_read2_b32 v[242:243], v244 offset0:1 offset1:0
	s_waitcnt lgkmcnt(14)
	v_add_f32_e32 v119, v82, v198
	v_add_f32_e32 v114, v83, v199
	s_waitcnt lgkmcnt(13)
	v_add_f32_e32 v118, v84, v200
	v_add_f32_e32 v113, v85, v201
	s_waitcnt lgkmcnt(12)
	v_add_f32_e32 v117, v86, v202
	v_add_f32_e32 v112, v87, v203
	s_waitcnt lgkmcnt(11)
	v_add_f32_e32 v115, v88, v204
	v_add_f32_e32 v85, v89, v205
	s_waitcnt lgkmcnt(10)
	v_add_f32_e32 v88, v90, v206
	v_add_f32_e32 v83, v91, v207
	s_waitcnt lgkmcnt(9)
	v_add_f32_e32 v87, v92, v208
	v_add_f32_e32 v81, v93, v209
	s_waitcnt lgkmcnt(8)
	v_add_f32_e32 v86, v94, v210
	v_add_f32_e32 v80, v95, v211
	s_waitcnt lgkmcnt(7)
	v_add_f32_e32 v84, v64, v212
	v_add_f32_e32 v82, v65, v213
	s_waitcnt lgkmcnt(6)
	v_add_f32_e32 v89, v66, v214
	v_add_f32_e32 v65, v67, v215
	s_waitcnt lgkmcnt(5)
	v_add_f32_e32 v67, v68, v216
	v_add_f32_e32 v66, v69, v217
	s_waitcnt lgkmcnt(4)
	v_add_f32_e32 v69, v70, v218
	v_add_f32_e32 v68, v71, v219
	s_waitcnt lgkmcnt(3)
	v_add_f32_e32 v71, v72, v236
	v_add_f32_e32 v70, v73, v237
	s_waitcnt lgkmcnt(2)
	v_add_f32_e32 v73, v74, v238
	v_add_f32_e32 v72, v75, v239
	s_waitcnt lgkmcnt(1)
	v_add_f32_e32 v92, v76, v240
	v_add_f32_e32 v91, v77, v241
	s_waitcnt lgkmcnt(0)
	v_add_f32_e32 v122, v78, v242
	v_add_f32_e32 v121, v79, v243
	v_max3_f32 v64, v120, s93, v116
	v_max3_f32 v64, v64, v119, v114
	v_max3_f32 v64, v64, v118, v113
	v_max3_f32 v64, v64, v117, v112
	v_max3_f32 v64, v64, v115, v85
	v_max3_f32 v64, v64, v88, v83
	v_max3_f32 v64, v64, v87, v81
	v_max3_f32 v64, v64, v86, v80
	v_max3_f32 v64, v64, v84, v82
	v_max3_f32 v64, v64, v89, v65
	v_max3_f32 v64, v64, v67, v66
	v_max3_f32 v64, v64, v69, v68
	v_and_b32_e32 v75, 64, v231
	v_max3_f32 v64, v64, v71, v70
	v_xor_b32_e32 v74, 32, v231
	v_add_u32_e32 v75, 64, v75
	v_max3_f32 v64, v64, v73, v72
	v_cmp_lt_i32_e32 vcc, v74, v75
	v_max3_f32 v64, v64, v92, v91
	v_max3_f32 v64, v64, v122, v121
	v_cndmask_b32_e32 v74, v231, v74, vcc
	v_lshlrev_b32_e32 v74, 2, v74
	v_mov_b32_e32 v74, v64
	s_nop 1
	v_permlane32_swap_b32_e32 v74, v64
	s_waitcnt lgkmcnt(0)
	v_max_f32_e32 v64, v64, v74
	v_add_f32_e32 v74, 0x41000000, v154
	v_cmp_gt_f32_e32 vcc, v64, v74
	s_nop 1
	v_cndmask_b32_e32 v150, v154, v64, vcc
	v_sub_f32_e32 v64, v154, v150
	v_exp_f32_e32 v64, v64
	s_nop 0
	v_cmp_neq_f32_e32 vcc, 1.0, v64
	s_cbranch_vccz .LBB0_975
	v_pk_mul_f32 v[62:63], v[62:63], v[64:65] op_sel_hi:[1,0]
	v_pk_mul_f32 v[60:61], v[60:61], v[64:65] op_sel_hi:[1,0]
	v_pk_mul_f32 v[58:59], v[58:59], v[64:65] op_sel_hi:[1,0]
	v_pk_mul_f32 v[56:57], v[56:57], v[64:65] op_sel_hi:[1,0]
	v_pk_mul_f32 v[54:55], v[54:55], v[64:65] op_sel_hi:[1,0]
	v_pk_mul_f32 v[52:53], v[52:53], v[64:65] op_sel_hi:[1,0]
	v_pk_mul_f32 v[50:51], v[50:51], v[64:65] op_sel_hi:[1,0]
	v_pk_mul_f32 v[48:49], v[48:49], v[64:65] op_sel_hi:[1,0]
	v_pk_mul_f32 v[46:47], v[46:47], v[64:65] op_sel_hi:[1,0]
	v_pk_mul_f32 v[44:45], v[44:45], v[64:65] op_sel_hi:[1,0]
	v_pk_mul_f32 v[42:43], v[42:43], v[64:65] op_sel_hi:[1,0]
	v_pk_mul_f32 v[40:41], v[40:41], v[64:65] op_sel_hi:[1,0]
	v_pk_mul_f32 v[38:39], v[38:39], v[64:65] op_sel_hi:[1,0]
	v_pk_mul_f32 v[36:37], v[36:37], v[64:65] op_sel_hi:[1,0]
	v_pk_mul_f32 v[34:35], v[34:35], v[64:65] op_sel_hi:[1,0]
	v_pk_mul_f32 v[32:33], v[32:33], v[64:65] op_sel_hi:[1,0]
	v_pk_mul_f32 v[30:31], v[30:31], v[64:65] op_sel_hi:[1,0]
	v_pk_mul_f32 v[28:29], v[28:29], v[64:65] op_sel_hi:[1,0]
	v_pk_mul_f32 v[26:27], v[26:27], v[64:65] op_sel_hi:[1,0]
	v_pk_mul_f32 v[24:25], v[24:25], v[64:65] op_sel_hi:[1,0]
	v_pk_mul_f32 v[22:23], v[22:23], v[64:65] op_sel_hi:[1,0]
	v_pk_mul_f32 v[20:21], v[20:21], v[64:65] op_sel_hi:[1,0]
	v_pk_mul_f32 v[18:19], v[18:19], v[64:65] op_sel_hi:[1,0]
	v_pk_mul_f32 v[16:17], v[16:17], v[64:65] op_sel_hi:[1,0]
	v_pk_mul_f32 v[14:15], v[14:15], v[64:65] op_sel_hi:[1,0]
	v_pk_mul_f32 v[12:13], v[12:13], v[64:65] op_sel_hi:[1,0]
	v_pk_mul_f32 v[10:11], v[10:11], v[64:65] op_sel_hi:[1,0]
	v_pk_mul_f32 v[8:9], v[8:9], v[64:65] op_sel_hi:[1,0]
	v_pk_mul_f32 v[6:7], v[6:7], v[64:65] op_sel_hi:[1,0]
	v_pk_mul_f32 v[4:5], v[4:5], v[64:65] op_sel_hi:[1,0]
	v_pk_mul_f32 v[2:3], v[2:3], v[64:65] op_sel_hi:[1,0]
	v_pk_mul_f32 v[0:1], v[0:1], v[64:65] op_sel_hi:[1,0]
	s_branch .LBB0_975
